# prep step 1 (conv+silu) rewritten: all 8 waves share the rows, loads for the next unit issued before the copy-out stores
# speedup vs baseline: 1.0096x; 1.0096x over previous
.LBB0_169:
	s_and_b64 vcc, exec, s[0:1]
	s_cbranch_vccz .LBB0_341
	v_readlane_b32 s0, v254, 51
	s_cmp_gt_i32 s0, 0
	s_mov_b64 s[0:1], -1
	s_cbranch_scc0 .LBB0_361
	v_readlane_b32 s0, v254, 51
	s_cmp_gt_i32 s0, 1
	s_mov_b64 s[0:1], -1
	s_cbranch_scc0 .LBB0_343
	v_writelane_b32 v254, s82, 54
	s_cmpk_gt_i32 s80, 0x7ff
	s_movk_i32 s76, 0x1800
	v_writelane_b32 v254, s83, 55
	s_mov_b32 s21, 0x3fb8aa3b
	s_mov_b32 s22, 0xc2ce8ed0
	s_cbranch_scc1 .LBB0_342
	s_add_u32 s70, s2, 0x9c00000
	s_addc_u32 s71, s3, 0
	s_add_u32 s0, s2, 0x200000
	s_addc_u32 s1, s3, 0
	v_writelane_b32 v254, s0, 56
	v_readlane_b32 s4, v253, 42
	v_readlane_b32 s8, v253, 46
	v_writelane_b32 v254, s1, 57
	v_readlane_b32 s9, v253, 47
	v_readlane_b32 s0, v254, 49
	v_readlane_b32 s1, v254, 50
	s_mov_b32 s20, s0
	s_mul_i32 s1, s20, 0x6000
	s_mul_hi_i32 s0, s0, 0x6000
	s_add_u32 s72, s8, s1
	s_addc_u32 s73, s9, s0
	s_add_u32 s0, s2, 0x300000
	v_writelane_b32 v254, s0, 58
	s_addc_u32 s0, s3, 0
	v_readlane_b32 s5, v253, 43
	v_readlane_b32 s11, v253, 49
	v_writelane_b32 v254, s0, 59
	s_add_u32 s4, s2, 0x1bc00000
	s_addc_u32 s5, s3, 0
	v_readlane_b32 s11, v254, 48
	v_readlane_b32 s14, v253, 52
	v_readlane_b32 s15, v253, 53
	s_movk_i32 s0, 0x17f
	s_cmp_eq_u32 s11, 7
	v_cmp_lt_i32_e64 s[38:39], s0, v158
	s_cselect_b64 s[14:15], -1, 0
	s_lshl_b32 s0, s20, 2
	v_writelane_b32 v254, s0, 60
	s_mov_b32 s0, 0x2aaaaaab
	v_mul_hi_i32 v0, v158, s0
	v_lshrrev_b32_e32 v2, 31, v0
	v_ashrrev_i32_e32 v0, 3, v0
	v_add_u32_e32 v4, v0, v2
	v_mul_lo_u32 v0, v4, 48
	v_sub_u32_e32 v0, v158, v0
	v_ashrrev_i32_e32 v2, 4, v0
	v_and_b32_e32 v3, 15, v0
	v_cmp_gt_i32_e32 vcc, 2, v2
	v_cmp_eq_u32_e64 s[0:1], 0, v3
	s_and_b64 s[8:9], vcc, s[0:1]
	s_lshl_b32 s0, s11, 3
	s_bfe_u32 s1, s37, 0x20006
	s_cmp_lt_u32 s11, 4
	v_readlane_b32 s6, v253, 44
	v_readlane_b32 s16, v253, 54
	v_readlane_b32 s17, v253, 55
	s_cselect_b64 s[44:45], -1, 0
	s_cmp_gt_u32 s11, 3
	v_cmp_gt_u32_e64 s[16:17], 16, v0
	v_lshrrev_b32_e32 v0, 1, v158
	v_and_b32_e32 v178, 15, v158
	s_cselect_b64 s[60:61], -1, 0
	s_lshl_b32 s6, s1, 4
	v_and_b32_e32 v16, 4, v0
	v_or_b32_e32 v0, s6, v178
	v_mul_u32_u24_e32 v179, 0x110, v0
	v_lshrrev_b32_e32 v0, 2, v158
	v_lshlrev_b32_e32 v14, 1, v160
	v_and_or_b32 v181, v0, 12, s6
	v_and_b32_e32 v0, 3, v158
	v_and_b32_e32 v182, 0x7f, v158
	v_lshlrev_b32_e32 v8, 2, v158
	v_readlane_b32 s7, v253, 45
	v_readlane_b32 s18, v253, 56
	v_readlane_b32 s19, v253, 57
	v_lshlrev_b32_e32 v117, 3, v3
	v_and_or_b32 v5, v14, 24, v0
	s_cmp_gt_i32 s11, 3
	v_lshlrev_b32_e32 v0, 7, v182
	v_and_b32_e32 v183, 0x7c, v8
	v_lshl_or_b32 v125, v2, 9, v117
	v_cmp_eq_u32_e64 s[18:19], 1, v2
	v_lshlrev_b32_e32 v159, 8, v2
	s_cselect_b64 s[40:41], -1, 0
	v_lshl_add_u64 v[2:3], s[2:3], 0, v[0:1]
	s_mov_b64 s[6:7], 0x19c00000
	s_cmp_lt_u32 s11, 2
	v_lshlrev_b32_e32 v0, 2, v183
	v_lshl_add_u64 v[82:83], v[2:3], 0, s[6:7]
	s_cselect_b64 s[48:49], -1, 0
	v_lshl_add_u64 v[2:3], s[2:3], 0, v[0:1]
	v_lshlrev_b32_e32 v0, 3, v158
	s_and_b64 s[6:7], s[48:49], exec
	v_and_b32_e32 v7, 0x60, v0
	v_lshlrev_b32_e32 v0, 4, v158
	s_mov_b64 s[6:7], 0x1c00000
	v_and_b32_e32 v0, 0xf0, v0
	v_lshl_add_u64 v[84:85], v[2:3], 0, s[6:7]
	v_lshl_add_u64 v[2:3], s[2:3], 0, v[0:1]
	s_mov_b64 s[6:7], 0x17c00000
	v_lshl_add_u64 v[86:87], v[2:3], 0, s[6:7]
	v_cmp_eq_u32_e64 s[6:7], 0, v160
	s_cselect_b32 s20, 0, 0x140
	s_cmp_lg_u32 s1, 0
	v_writelane_b32 v254, s6, 61
	s_cselect_b64 s[42:43], -1, 0
	s_cmp_gt_u32 s1, 1
	v_writelane_b32 v254, s7, 62
	v_cmp_gt_u32_e64 s[6:7], 2, v160
	s_cselect_b64 s[46:47], -1, 0
	v_lshlrev_b32_e32 v0, 1, v5
	v_writelane_b32 v254, s6, 63
	v_lshlrev_b32_e32 v78, 3, v4
	v_lshl_add_u64 v[106:107], s[4:5], 0, v[0:1]
	v_writelane_b32 v255, s7, 0
	v_cmp_gt_u32_e64 s[6:7], 4, v160
	v_mov_b32_e32 v5, v1
	v_lshlrev_b32_e32 v9, 2, v160
	v_writelane_b32 v255, s6, 1
	v_and_b32_e32 v15, 24, v9
	v_and_b32_e32 v17, 2, v14
	v_writelane_b32 v255, s7, 2
	v_cmp_gt_u32_e64 s[6:7], 8, v160
	v_or_b32_e32 v192, 16, v178
	v_or_b32_e32 v190, 2, v181
	v_writelane_b32 v255, s6, 3
	v_or_b32_e32 v191, 3, v181
	v_or_b32_e32 v193, 32, v178
	v_writelane_b32 v255, s7, 4
	v_cmp_gt_u32_e64 s[6:7], 16, v160
	v_or_b32_e32 v194, 48, v160
	v_or_b32_e32 v189, 1, v181
	v_writelane_b32 v255, s6, 5
	v_add_u32_e32 v18, 0xffffff00, v158
	v_ashrrev_i32_e32 v3, 4, v18
	v_writelane_b32 v255, s7, 6
	v_cmp_gt_u32_e64 s[6:7], 32, v160
	v_and_b32_e32 v130, 0xffffffe0, v3
	v_bfe_u32 v3, v158, 7, 2
	v_writelane_b32 v255, s6, 7
	v_readlane_b32 s10, v253, 48
	s_movk_i32 s10, 0x210
	v_writelane_b32 v255, s7, 8
	s_movk_i32 s6, 0x1080
	v_mul_lo_u32 v185, v4, s6
	s_add_u32 s6, s2, 0x1bc00040
	s_addc_u32 s7, s3, 0
	s_cmp_eq_u32 s1, 3
	v_lshlrev_b32_e32 v4, 7, v181
	v_lshl_add_u64 v[110:111], s[6:7], 0, v[0:1]
	v_or_b32_e32 v0, 8, v0
	s_cselect_b64 s[62:63], -1, 0
	s_ashr_i32 s81, s80, 31
	s_ashr_i32 s1, s0, 31
	v_lshl_add_u64 v[10:11], s[4:5], 0, v[4:5]
	v_lshl_add_u64 v[112:113], s[4:5], 0, v[0:1]
	s_lshl_b64 s[4:5], s[80:81], 14
	s_lshl_b64 s[0:1], s[0:1], 8
	v_lshl_add_u64 v[12:13], s[6:7], 0, v[4:5]
	s_add_u32 s0, s4, s0
	s_movk_i32 s4, 0x60
	v_lshl_add_u64 v[114:115], s[6:7], 0, v[0:1]
	s_addc_u32 s1, s5, s1
	v_lshl_add_u64 v[118:119], v[10:11], 0, v[0:1]
	v_lshl_add_u64 v[120:121], v[12:13], 0, v[0:1]
	v_and_or_b32 v0, v14, s4, v15
	v_or3_b32 v0, v0, v16, v17
	s_add_u32 s0, s2, s0
	v_lshlrev_b32_e32 v0, 1, v0
	s_addc_u32 s1, s3, s1
	v_lshl_add_u64 v[122:123], s[0:1], 0, v[0:1]
	s_mul_i32 s0, s11, 0x880
	v_add_u32_e32 v232, s0, v9
	s_mul_i32 s0, s11, 0x1080
	v_lshl_add_u32 v233, v160, 3, s0
	v_cmp_le_u32_e64 s[0:1], v192, v181
	v_lshl_add_u64 v[108:109], v[106:107], 0, v[4:5]
	v_lshl_add_u64 v[128:129], v[110:111], 0, v[4:5]
	v_writelane_b32 v255, s0, 9
	v_lshlrev_b32_e32 v5, 2, v3
	v_lshlrev_b32_e32 v4, 3, v3
	v_writelane_b32 v255, s1, 10
	v_cmp_lt_u32_e64 s[0:1], v192, v181
	v_add_u32_e32 v3, 0x100, v158
	v_bfe_u32 v10, v3, 7, 2
	v_writelane_b32 v255, s0, 11
	v_ashrrev_i32_e32 v3, 4, v3
	v_ashrrev_i32_e32 v14, 5, v158
	v_writelane_b32 v255, s1, 12
	v_cmp_lt_u32_e64 s[0:1], v192, v190
	v_and_b32_e32 v134, 0xffffffe0, v3
	v_add_u32_e32 v3, 0x200, v158
	v_writelane_b32 v255, s0, 13
	v_ashrrev_i32_e32 v15, 31, v14
	v_mul_lo_u32 v227, v14, s10
	v_writelane_b32 v255, s1, 14
	v_cmp_gt_u32_e64 s[0:1], v192, v191
	v_lshlrev_b64 v[138:139], 9, v[14:15]
	v_ashrrev_i32_e32 v14, 5, v3
	v_writelane_b32 v255, s0, 15
	v_and_or_b32 v6, s37, 64, v160
	v_ashrrev_i32_e32 v12, 4, v3
	v_writelane_b32 v255, s1, 16
	v_cmp_lt_u32_e64 s[0:1], v192, v191
	v_ashrrev_i32_e32 v15, 31, v14
	v_add_u32_e32 v3, 0x400, v158
	v_writelane_b32 v255, s0, 17
	s_ashr_i32 s37, s36, 31
	v_ashrrev_i32_e32 v2, 4, v158
	v_writelane_b32 v255, s1, 18
	v_cmp_gt_u32_e64 s[0:1], v193, v181
	v_mul_lo_u32 v228, v14, s10
	v_lshlrev_b64 v[140:141], 9, v[14:15]
	v_writelane_b32 v255, s0, 19
	v_ashrrev_i32_e32 v14, 5, v3
	v_bfe_u32 v0, v18, 7, 2
	v_writelane_b32 v255, s1, 20
	v_cmp_le_u32_e64 s[0:1], v193, v181
	v_and_b32_e32 v132, 0xffffffe0, v2
	v_and_b32_e32 v136, 0xffffffe0, v12
	v_writelane_b32 v255, s0, 21
	v_ashrrev_i32_e32 v15, 31, v14
	v_add_u32_e32 v3, 0x600, v158
	v_writelane_b32 v255, s1, 22
	v_cmp_lt_u32_e64 s[0:1], v193, v181
	v_cmp_gt_u32_e64 s[26:27], v178, v181
	v_lshl_or_b32 v196, v0, 2, v130
	v_writelane_b32 v255, s0, 23
	v_or_b32_e32 v202, v5, v132
	v_lshl_or_b32 v208, v10, 2, v134
	v_writelane_b32 v255, s1, 24
	v_cmp_gt_u32_e64 s[0:1], v193, v190
	v_or_b32_e32 v221, v5, v136
	v_mul_lo_u32 v229, v14, s10
	v_writelane_b32 v255, s0, 25
	v_lshlrev_b64 v[142:143], 9, v[14:15]
	v_ashrrev_i32_e32 v14, 5, v3
	v_writelane_b32 v255, s1, 26
	v_cmp_lt_u32_e64 s[0:1], v193, v190
	v_add_u32_e32 v80, -3, v78
	v_and_b32_e32 v8, 12, v8
	v_writelane_b32 v255, s0, 27
	v_add_u32_e32 v88, -2, v78
	v_add_u32_e32 v90, -1, v78
	v_writelane_b32 v255, s1, 28
	v_cmp_gt_u32_e64 s[0:1], v193, v191
	v_or_b32_e32 v92, 1, v78
	v_or_b32_e32 v94, 2, v78
	v_writelane_b32 v255, s0, 29
	v_or_b32_e32 v96, 3, v78
	v_or_b32_e32 v98, 4, v78
	v_writelane_b32 v255, s1, 30
	v_cmp_lt_u32_e64 s[0:1], v193, v191
	v_or_b32_e32 v100, 5, v78
	v_or_b32_e32 v102, 6, v78
	v_writelane_b32 v255, s0, 31
	v_or_b32_e32 v104, 7, v78
	v_mul_lo_u32 v197, v196, s10
	v_writelane_b32 v255, s1, 32
	v_cmp_gt_u32_e64 s[0:1], v194, v181
	v_lshlrev_b32_e32 v0, 3, v0
	v_mul_lo_u32 v203, v202, s10
	v_writelane_b32 v255, s0, 33
	v_mul_lo_u32 v209, v208, s10
	v_lshlrev_b32_e32 v10, 3, v10
	v_writelane_b32 v255, s1, 34
	v_cmp_le_u32_e64 s[0:1], v194, v181
	v_mul_lo_u32 v222, v221, s10
	v_ashrrev_i32_e32 v15, 31, v14
	v_writelane_b32 v255, s0, 35
	v_ashrrev_i32_e32 v3, 31, v2
	v_ashrrev_i32_e32 v13, 31, v12
	v_writelane_b32 v255, s1, 36
	v_cmp_lt_u32_e64 s[0:1], v194, v181
	v_add_u32_e32 v127, 0x400, v125
	v_and_b32_e32 v180, 48, v158
	v_writelane_b32 v255, s0, 37
	v_cmp_eq_u32_e64 s[24:25], 0, v18
	v_mul_lo_u32 v184, v2, s10
	v_writelane_b32 v255, s1, 38
	v_cmp_gt_u32_e64 s[0:1], v194, v189
	v_ashrrev_i32_e32 v81, 31, v80
	v_ashrrev_i32_e32 v89, 31, v88
	v_writelane_b32 v255, s0, 39
	v_ashrrev_i32_e32 v91, 31, v90
	v_ashrrev_i32_e32 v79, 31, v78
	v_writelane_b32 v255, s1, 40
	v_cmp_gt_u32_e64 s[0:1], v194, v190
	v_ashrrev_i32_e32 v93, 31, v92
	v_ashrrev_i32_e32 v95, 31, v94
	v_writelane_b32 v255, s0, 41
	v_ashrrev_i32_e32 v97, 31, v96
	v_ashrrev_i32_e32 v99, 31, v98
	v_writelane_b32 v255, s1, 42
	v_cmp_lt_u32_e64 s[0:1], v194, v190
	v_ashrrev_i32_e32 v101, 31, v100
	v_ashrrev_i32_e32 v103, 31, v102
	v_writelane_b32 v255, s0, 43
	v_ashrrev_i32_e32 v105, 31, v104
	v_mul_lo_u32 v186, v92, s10
	v_writelane_b32 v255, s1, 44
	v_cmp_gt_u32_e64 s[0:1], v194, v191
	v_mul_u32_u24_e32 v187, 0x110, v178
	v_cmp_le_u32_e64 s[66:67], v178, v181
	v_writelane_b32 v255, s0, 45
	v_cmp_lt_u32_e64 s[56:57], v178, v181
	v_mul_u32_u24_e32 v188, 0x110, v181
	v_writelane_b32 v255, s1, 46
	v_cmp_lt_u32_e64 s[0:1], v194, v191
	v_cmp_gt_u32_e64 s[58:59], v178, v189
	v_lshlrev_b32_e32 v116, 6, v189
	v_writelane_b32 v255, s0, 47
	v_cmp_gt_u32_e64 s[4:5], v178, v190
	v_lshlrev_b32_e32 v124, 6, v190
	v_writelane_b32 v255, s1, 48
	s_lshl_b64 s[0:1], s[36:37], 14
	v_writelane_b32 v255, s0, 49
	v_lshlrev_b32_e32 v126, 6, v191
	v_mul_u32_u24_e32 v195, 0x110, v194
	v_writelane_b32 v255, s1, 50
	v_writelane_b32 v255, s26, 51
	v_add_u32_e32 v252, 0x210, v197
	v_or_b32_e32 v215, 2, v196
	v_add_u32_e32 v200, 0x420, v197
	v_add_u32_e32 v201, 0x630, v197
	v_ashrrev_i32_e32 v131, 31, v130
	v_add_u32_e32 v204, 0x210, v203
	v_or_b32_e32 v205, 2, v202
	v_add_u32_e32 v206, 0x420, v203
	v_add_u32_e32 v207, 0x630, v203
	v_ashrrev_i32_e32 v133, 31, v132
	v_add_u32_e32 v210, 0x210, v209
	v_or_b32_e32 v211, 2, v208
	v_add_u32_e32 v212, 0x420, v209
	v_add_u32_e32 v213, 0x630, v209
	v_ashrrev_i32_e32 v135, 31, v134
	v_add_u32_e32 v223, 0x210, v222
	v_or_b32_e32 v224, 2, v221
	v_add_u32_e32 v225, 0x420, v222
	v_add_u32_e32 v226, 0x630, v222
	v_ashrrev_i32_e32 v137, 31, v136
	v_mul_lo_u32 v230, v14, s10
	v_lshlrev_b64 v[144:145], 9, v[14:15]
	v_lshlrev_b64 v[162:163], 8, v[2:3]
	v_mul_lo_u32 v231, v12, s10
	v_lshlrev_b64 v[164:165], 8, v[12:13]
	s_lshl_b32 s88, s11, 5
	v_mov_b32_e32 v234, 0
	v_lshlrev_b32_e32 v0, 1, v0
	v_lshlrev_b32_e32 v166, 1, v4
	v_lshlrev_b32_e32 v168, 1, v10
	v_lshlrev_b32_e32 v235, 2, v6
	v_lshlrev_b32_e32 v236, 2, v7
	v_lshlrev_b32_e32 v237, 2, v8
	v_cmp_lt_u32_e64 s[6:7], v178, v190
	v_cmp_gt_u32_e64 s[10:11], v178, v191
	v_cmp_lt_u32_e64 s[84:85], v178, v191
	v_cmp_gt_u32_e64 s[74:75], v192, v181
	v_cmp_gt_u32_e64 s[82:83], v192, v189
	v_cmp_gt_u32_e64 s[78:79], v192, v190
	v_cmp_gt_u32_e64 s[86:87], v193, v189
	s_mov_b32 s64, s80
	v_writelane_b32 v255, s27, 52
	v_readlane_b32 s12, v253, 50
	v_readlane_b32 s13, v253, 51
	s_mov_b32 s98, s64
	s_cmp_lt_u32 s88, 0x80
	s_cbranch_scc0 .Lcvi_v_f
	s_lshr_b32 s28, s88, 5
	v_lshrrev_b32_e32 v3, 4, v160
	s_and_b32 s29, s28, 1
	s_lshl_b32 s29, s29, 5
	v_lshl_add_u32 v4, v3, 3, s29
	s_lshr_b32 s99, s28, 1
	s_lshl_b32 s99, s99, 9
	s_bfe_u32 s28, s98, 0x20006
	s_lshl_b32 s28, s28, 7
	s_add_u32 s99, s99, s28
	v_and_b32_e32 v2, 15, v160
	v_lshl_add_u32 v5, v2, 3, s99
	v_lshlrev_b32_e32 v16, 2, v5
	v_add_u32_e32 v24, 0x1800, v16
	v_add_u32_e32 v34, 0x3000, v16
	v_add_u32_e32 v42, 0x4800, v16
	s_lshr_b32 s28, s98, 8
	s_lshl_b32 s28, s28, 12
	s_lshl_b32 s29, s98, 6
	s_and_b32 s29, s29, 0xfc0
	s_or_b32 s28, s28, s29
	s_sub_u32 s28, s28, 3
	v_add_u32_e32 v3, s28, v4
	v_lshlrev_b32_e32 v5, 1, v5
	v_add_u32_e32 v5, 0x800, v5
	v_mad_i32_i24 v50, v3, s76, v5
	v_add_u32_e32 v54, 0x1800, v50
	v_add_u32_e32 v58, 0x3000, v50
	v_add_u32_e32 v62, 0x4800, v50
	v_add_u32_e32 v66, 0x6000, v50
	v_add_u32_e32 v70, 0x7800, v50
	v_add_u32_e32 v74, 0x9000, v50
	v_add_u32_e32 v78, 0xa800, v50
	v_add_u32_e32 v88, 0xc000, v50
	v_add_u32_e32 v92, 0xd800, v50
	v_add_u32_e32 v96, 0xf000, v50
	v_max_i32_e32 v50, 0, v50
	v_max_i32_e32 v54, 0, v54
	v_max_i32_e32 v58, 0, v58
	global_load_dwordx4 v[20:23], v16, s[72:73] offset:16
	global_load_dwordx4 v[16:19], v16, s[72:73]
	global_load_dwordx4 v[30:33], v24, s[72:73] offset:16
	global_load_dwordx4 v[24:27], v24, s[72:73]
	global_load_dwordx4 v[38:41], v34, s[72:73] offset:16
	global_load_dwordx4 v[34:37], v34, s[72:73]
	global_load_dwordx4 v[46:49], v42, s[72:73] offset:16
	global_load_dwordx4 v[42:45], v42, s[72:73]
	global_load_dwordx4 v[50:53], v50, s[70:71]
	global_load_dwordx4 v[54:57], v54, s[70:71]
	global_load_dwordx4 v[58:61], v58, s[70:71]
	global_load_dwordx4 v[62:65], v62, s[70:71]
	global_load_dwordx4 v[66:69], v66, s[70:71]
	global_load_dwordx4 v[70:73], v70, s[70:71]
	global_load_dwordx4 v[74:77], v74, s[70:71]
	global_load_dwordx4 v[78:81], v78, s[70:71]
	global_load_dwordx4 v[88:91], v88, s[70:71]
	global_load_dwordx4 v[92:95], v92, s[70:71]
	global_load_dwordx4 v[96:99], v96, s[70:71]
	s_branch .Lcvi_done_f
.Lcvi_v_f:
	s_lshr_b32 s28, s88, 5
	v_lshrrev_b32_e32 v3, 4, v160
	s_sub_u32 s29, s28, 4
	s_lshl_b32 s29, s29, 4
	v_lshl_add_u32 v4, v3, 2, s29
	s_movk_i32 s99, 0x400
	s_bfe_u32 s28, s98, 0x20006
	s_lshl_b32 s28, s28, 7
	s_add_u32 s99, s99, s28
	v_and_b32_e32 v2, 15, v160
	v_lshl_add_u32 v5, v2, 3, s99
	v_lshlrev_b32_e32 v16, 2, v5
	v_add_u32_e32 v24, 0x1800, v16
	v_add_u32_e32 v34, 0x3000, v16
	v_add_u32_e32 v42, 0x4800, v16
	s_lshr_b32 s28, s98, 8
	s_lshl_b32 s28, s28, 12
	s_lshl_b32 s29, s98, 6
	s_and_b32 s29, s29, 0xfc0
	s_or_b32 s28, s28, s29
	s_sub_u32 s28, s28, 3
	v_add_u32_e32 v3, s28, v4
	v_lshlrev_b32_e32 v5, 1, v5
	v_add_u32_e32 v5, 0x800, v5
	v_mad_i32_i24 v50, v3, s76, v5
	v_add_u32_e32 v54, 0x1800, v50
	v_add_u32_e32 v58, 0x3000, v50
	v_add_u32_e32 v62, 0x4800, v50
	v_add_u32_e32 v66, 0x6000, v50
	v_add_u32_e32 v70, 0x7800, v50
	v_add_u32_e32 v74, 0x9000, v50
	v_max_i32_e32 v50, 0, v50
	v_max_i32_e32 v54, 0, v54
	v_max_i32_e32 v58, 0, v58
	global_load_dwordx4 v[20:23], v16, s[72:73] offset:16
	global_load_dwordx4 v[16:19], v16, s[72:73]
	global_load_dwordx4 v[30:33], v24, s[72:73] offset:16
	global_load_dwordx4 v[24:27], v24, s[72:73]
	global_load_dwordx4 v[38:41], v34, s[72:73] offset:16
	global_load_dwordx4 v[34:37], v34, s[72:73]
	global_load_dwordx4 v[46:49], v42, s[72:73] offset:16
	global_load_dwordx4 v[42:45], v42, s[72:73]
	global_load_dwordx4 v[50:53], v50, s[70:71]
	global_load_dwordx4 v[54:57], v54, s[70:71]
	global_load_dwordx4 v[58:61], v58, s[70:71]
	global_load_dwordx4 v[62:65], v62, s[70:71]
	global_load_dwordx4 v[66:69], v66, s[70:71]
	global_load_dwordx4 v[70:73], v70, s[70:71]
	global_load_dwordx4 v[74:77], v74, s[70:71]
.Lcvi_done_f:
	s_waitcnt vmcnt(0)
	s_branch .LBB0_175
.LBB0_174:
	s_add_i32 s98, s64, s36
	s_cmpk_gt_i32 s98, 0x7ff
	s_cbranch_scc1 .Lcvi_done_n
	s_cmp_lt_u32 s88, 0x80
	s_cbranch_scc0 .Lcvi_v_n
	s_lshr_b32 s28, s88, 5
	v_lshrrev_b32_e32 v3, 4, v160
	s_and_b32 s29, s28, 1
	s_lshl_b32 s29, s29, 5
	v_lshl_add_u32 v4, v3, 3, s29
	s_lshr_b32 s99, s28, 1
	s_lshl_b32 s99, s99, 9
	s_bfe_u32 s28, s98, 0x20006
	s_lshl_b32 s28, s28, 7
	s_add_u32 s99, s99, s28
	v_and_b32_e32 v2, 15, v160
	v_lshl_add_u32 v5, v2, 3, s99
	v_lshlrev_b32_e32 v16, 2, v5
	v_add_u32_e32 v24, 0x1800, v16
	v_add_u32_e32 v34, 0x3000, v16
	v_add_u32_e32 v42, 0x4800, v16
	s_lshr_b32 s28, s98, 8
	s_lshl_b32 s28, s28, 12
	s_lshl_b32 s29, s98, 6
	s_and_b32 s29, s29, 0xfc0
	s_or_b32 s28, s28, s29
	s_sub_u32 s28, s28, 3
	v_add_u32_e32 v3, s28, v4
	v_lshlrev_b32_e32 v5, 1, v5
	v_add_u32_e32 v5, 0x800, v5
	v_mad_i32_i24 v50, v3, s76, v5
	v_add_u32_e32 v54, 0x1800, v50
	v_add_u32_e32 v58, 0x3000, v50
	v_add_u32_e32 v62, 0x4800, v50
	v_add_u32_e32 v66, 0x6000, v50
	v_add_u32_e32 v70, 0x7800, v50
	v_add_u32_e32 v74, 0x9000, v50
	v_add_u32_e32 v78, 0xa800, v50
	v_add_u32_e32 v88, 0xc000, v50
	v_add_u32_e32 v92, 0xd800, v50
	v_add_u32_e32 v96, 0xf000, v50
	v_max_i32_e32 v50, 0, v50
	v_max_i32_e32 v54, 0, v54
	v_max_i32_e32 v58, 0, v58
	global_load_dwordx4 v[20:23], v16, s[72:73] offset:16
	global_load_dwordx4 v[16:19], v16, s[72:73]
	global_load_dwordx4 v[30:33], v24, s[72:73] offset:16
	global_load_dwordx4 v[24:27], v24, s[72:73]
	global_load_dwordx4 v[38:41], v34, s[72:73] offset:16
	global_load_dwordx4 v[34:37], v34, s[72:73]
	global_load_dwordx4 v[46:49], v42, s[72:73] offset:16
	global_load_dwordx4 v[42:45], v42, s[72:73]
	global_load_dwordx4 v[50:53], v50, s[70:71]
	global_load_dwordx4 v[54:57], v54, s[70:71]
	global_load_dwordx4 v[58:61], v58, s[70:71]
	global_load_dwordx4 v[62:65], v62, s[70:71]
	global_load_dwordx4 v[66:69], v66, s[70:71]
	global_load_dwordx4 v[70:73], v70, s[70:71]
	global_load_dwordx4 v[74:77], v74, s[70:71]
	global_load_dwordx4 v[78:81], v78, s[70:71]
	global_load_dwordx4 v[88:91], v88, s[70:71]
	global_load_dwordx4 v[92:95], v92, s[70:71]
	global_load_dwordx4 v[96:99], v96, s[70:71]
	s_branch .Lcvi_done_n

.LBB0_178:
	s_or_saveexec_b64 s[0:1], s[0:1]
	v_add_u32_e32 v240, 0x8400, v234
	v_add_u32_e32 v238, 0x10800, v234
	s_mov_b64 exec, -1
	s_cmp_lt_u32 s88, 0x80
	s_cbranch_scc0 .Lcv_vwaves
	s_lshr_b32 s28, s88, 5
	v_lshrrev_b32_e32 v181, 4, v160
	s_and_b32 s29, s28, 1
	s_lshl_b32 s29, s29, 5
	v_lshl_add_u32 v180, v181, 3, s29
	s_lshr_b32 s55, s28, 1
	v_and_b32_e32 v128, 15, v160
	s_mul_i32 s28, s55, 0x8400
	v_lshlrev_b32_e32 v178, 9, v180
	v_lshl_add_u32 v178, v180, 4, v178
	v_lshl_add_u32 v178, v128, 5, v178
	v_add3_u32 v178, v178, v234, s28
	s_lshl_b32 s28, s55, 8
	s_addk_i32 s28, 0x300
	v_lshl_add_u32 v179, v180, 2, v239
	v_add_u32_e32 v179, s28, v179
	s_waitcnt vmcnt(14)
	s_cmp_lg_u32 s37, 0
	s_cbranch_scc1 .Lcv_nz_a
	v_cmp_eq_u32_e32 vcc, 0, v180
	s_nop 1
	v_cndmask_b32_e64 v50, v50, 0, vcc
	v_cndmask_b32_e64 v51, v51, 0, vcc
	v_cndmask_b32_e64 v52, v52, 0, vcc
	v_cndmask_b32_e64 v53, v53, 0, vcc
	v_cndmask_b32_e64 v54, v54, 0, vcc
	v_cndmask_b32_e64 v55, v55, 0, vcc
	v_cndmask_b32_e64 v56, v56, 0, vcc
	v_cndmask_b32_e64 v57, v57, 0, vcc
	v_cndmask_b32_e64 v58, v58, 0, vcc
	v_cndmask_b32_e64 v59, v59, 0, vcc
	v_cndmask_b32_e64 v60, v60, 0, vcc
	v_cndmask_b32_e64 v61, v61, 0, vcc
.Lcv_nz_a:
	v_lshlrev_b32_e32 v2, 16, v50
	v_and_b32_e32 v3, 0xffff0000, v50
	v_lshlrev_b32_e32 v4, 16, v51
	v_and_b32_e32 v5, 0xffff0000, v51
	v_lshlrev_b32_e32 v6, 16, v52
	v_and_b32_e32 v7, 0xffff0000, v52
	v_lshlrev_b32_e32 v8, 16, v53
	v_and_b32_e32 v9, 0xffff0000, v53
	v_lshlrev_b32_e32 v10, 16, v54
	v_and_b32_e32 v11, 0xffff0000, v54
	v_lshlrev_b32_e32 v12, 16, v55
	v_and_b32_e32 v13, 0xffff0000, v55
	v_lshlrev_b32_e32 v14, 16, v56
	v_and_b32_e32 v15, 0xffff0000, v56
	v_lshlrev_b32_e32 v100, 16, v57
	v_and_b32_e32 v101, 0xffff0000, v57
	v_lshlrev_b32_e32 v102, 16, v58
	v_and_b32_e32 v103, 0xffff0000, v58
	v_lshlrev_b32_e32 v104, 16, v59
	v_and_b32_e32 v105, 0xffff0000, v59
	v_lshlrev_b32_e32 v106, 16, v60
	v_and_b32_e32 v107, 0xffff0000, v60
	v_lshlrev_b32_e32 v108, 16, v61
	v_and_b32_e32 v109, 0xffff0000, v61
	s_waitcnt vmcnt(13)
	v_lshlrev_b32_e32 v110, 16, v62
	v_and_b32_e32 v111, 0xffff0000, v62
	v_lshlrev_b32_e32 v112, 16, v63
	v_and_b32_e32 v113, 0xffff0000, v63
	v_lshlrev_b32_e32 v114, 16, v64
	v_and_b32_e32 v115, 0xffff0000, v64
	v_lshlrev_b32_e32 v116, 16, v65
	v_and_b32_e32 v117, 0xffff0000, v65
	v_pk_mul_f32 v[124:125], v[16:17], v[2:3]
	v_pk_mul_f32 v[126:127], v[18:19], v[4:5]
	v_pk_mul_f32 v[118:119], v[20:21], v[6:7]
	v_pk_mul_f32 v[120:121], v[22:23], v[8:9]
	v_pk_fma_f32 v[124:125], v[24:25], v[10:11], v[124:125]
	v_pk_fma_f32 v[126:127], v[26:27], v[12:13], v[126:127]
	v_pk_fma_f32 v[118:119], v[30:31], v[14:15], v[118:119]
	v_pk_fma_f32 v[120:121], v[32:33], v[100:101], v[120:121]
	v_pk_fma_f32 v[124:125], v[34:35], v[102:103], v[124:125]
	v_pk_fma_f32 v[126:127], v[36:37], v[104:105], v[126:127]
	v_pk_fma_f32 v[118:119], v[38:39], v[106:107], v[118:119]
	v_pk_fma_f32 v[120:121], v[40:41], v[108:109], v[120:121]
	v_pk_fma_f32 v[124:125], v[42:43], v[110:111], v[124:125]
	v_pk_fma_f32 v[126:127], v[44:45], v[112:113], v[126:127]
	v_pk_fma_f32 v[118:119], v[46:47], v[114:115], v[118:119]
	v_pk_fma_f32 v[120:121], v[48:49], v[116:117], v[120:121]
	v_mul_f32_e32 v2, 0xbfb8aa3b, v124
	v_mul_f32_e32 v3, 0xbfb8aa3b, v125
	v_mul_f32_e32 v4, 0xbfb8aa3b, v126
	v_mul_f32_e32 v5, 0xbfb8aa3b, v127
	v_mul_f32_e32 v6, 0xbfb8aa3b, v118
	v_mul_f32_e32 v7, 0xbfb8aa3b, v119
	v_mul_f32_e32 v8, 0xbfb8aa3b, v120
	v_mul_f32_e32 v9, 0xbfb8aa3b, v121
	v_exp_f32_e32 v2, v2
	v_exp_f32_e32 v3, v3
	v_exp_f32_e32 v4, v4
	v_exp_f32_e32 v5, v5
	v_exp_f32_e32 v6, v6
	v_exp_f32_e32 v7, v7
	v_exp_f32_e32 v8, v8
	v_exp_f32_e32 v9, v9
	v_add_f32_e32 v2, 1.0, v2
	v_add_f32_e32 v3, 1.0, v3
	v_add_f32_e32 v4, 1.0, v4
	v_add_f32_e32 v5, 1.0, v5
	v_add_f32_e32 v6, 1.0, v6
	v_add_f32_e32 v7, 1.0, v7
	v_add_f32_e32 v8, 1.0, v8
	v_add_f32_e32 v9, 1.0, v9
	v_rcp_f32_e32 v2, v2
	v_rcp_f32_e32 v3, v3
	v_rcp_f32_e32 v4, v4
	v_rcp_f32_e32 v5, v5
	v_rcp_f32_e32 v6, v6
	v_rcp_f32_e32 v7, v7
	v_rcp_f32_e32 v8, v8
	v_rcp_f32_e32 v9, v9
	v_pk_mul_f32 v[124:125], v[124:125], v[2:3]
	v_pk_mul_f32 v[126:127], v[126:127], v[4:5]
	v_pk_mul_f32 v[118:119], v[118:119], v[6:7]
	v_pk_mul_f32 v[120:121], v[120:121], v[8:9]
	ds_write_b128 v178, v[124:127] offset:0
	ds_write_b128 v178, v[118:121] offset:16
	v_mul_f32_e32 v170, v124, v124
	v_mul_f32_e32 v181, v118, v118
	v_fmac_f32_e32 v170, v125, v125
	v_fmac_f32_e32 v181, v119, v119
	v_fmac_f32_e32 v170, v126, v126
	v_fmac_f32_e32 v181, v120, v120
	v_fmac_f32_e32 v170, v127, v127
	v_fmac_f32_e32 v181, v121, v121
	v_add_f32_e32 v170, v170, v181
	s_waitcnt vmcnt(12)
	v_lshlrev_b32_e32 v2, 16, v66
	v_and_b32_e32 v3, 0xffff0000, v66
	v_lshlrev_b32_e32 v4, 16, v67
	v_and_b32_e32 v5, 0xffff0000, v67
	v_lshlrev_b32_e32 v6, 16, v68
	v_and_b32_e32 v7, 0xffff0000, v68
	v_lshlrev_b32_e32 v8, 16, v69
	v_and_b32_e32 v9, 0xffff0000, v69
	v_pk_mul_f32 v[124:125], v[16:17], v[10:11]
	v_pk_mul_f32 v[126:127], v[18:19], v[12:13]
	v_pk_mul_f32 v[118:119], v[20:21], v[14:15]
	v_pk_mul_f32 v[120:121], v[22:23], v[100:101]
	v_pk_fma_f32 v[124:125], v[24:25], v[102:103], v[124:125]
	v_pk_fma_f32 v[126:127], v[26:27], v[104:105], v[126:127]
	v_pk_fma_f32 v[118:119], v[30:31], v[106:107], v[118:119]
	v_pk_fma_f32 v[120:121], v[32:33], v[108:109], v[120:121]
	v_pk_fma_f32 v[124:125], v[34:35], v[110:111], v[124:125]
	v_pk_fma_f32 v[126:127], v[36:37], v[112:113], v[126:127]
	v_pk_fma_f32 v[118:119], v[38:39], v[114:115], v[118:119]
	v_pk_fma_f32 v[120:121], v[40:41], v[116:117], v[120:121]
	v_pk_fma_f32 v[124:125], v[42:43], v[2:3], v[124:125]
	v_pk_fma_f32 v[126:127], v[44:45], v[4:5], v[126:127]
	v_pk_fma_f32 v[118:119], v[46:47], v[6:7], v[118:119]
	v_pk_fma_f32 v[120:121], v[48:49], v[8:9], v[120:121]
	v_mul_f32_e32 v10, 0xbfb8aa3b, v124
	v_mul_f32_e32 v11, 0xbfb8aa3b, v125
	v_mul_f32_e32 v12, 0xbfb8aa3b, v126
	v_mul_f32_e32 v13, 0xbfb8aa3b, v127
	v_mul_f32_e32 v14, 0xbfb8aa3b, v118
	v_mul_f32_e32 v15, 0xbfb8aa3b, v119
	v_mul_f32_e32 v100, 0xbfb8aa3b, v120
	v_mul_f32_e32 v101, 0xbfb8aa3b, v121
	v_exp_f32_e32 v10, v10
	v_exp_f32_e32 v11, v11
	v_exp_f32_e32 v12, v12
	v_exp_f32_e32 v13, v13
	v_exp_f32_e32 v14, v14
	v_exp_f32_e32 v15, v15
	v_exp_f32_e32 v100, v100
	v_exp_f32_e32 v101, v101
	v_add_f32_e32 v10, 1.0, v10
	v_add_f32_e32 v11, 1.0, v11
	v_add_f32_e32 v12, 1.0, v12
	v_add_f32_e32 v13, 1.0, v13
	v_add_f32_e32 v14, 1.0, v14
	v_add_f32_e32 v15, 1.0, v15
	v_add_f32_e32 v100, 1.0, v100
	v_add_f32_e32 v101, 1.0, v101
	v_rcp_f32_e32 v10, v10
	v_rcp_f32_e32 v11, v11
	v_rcp_f32_e32 v12, v12
	v_rcp_f32_e32 v13, v13
	v_rcp_f32_e32 v14, v14
	v_rcp_f32_e32 v15, v15
	v_rcp_f32_e32 v100, v100
	v_rcp_f32_e32 v101, v101
	v_pk_mul_f32 v[124:125], v[124:125], v[10:11]
	v_pk_mul_f32 v[126:127], v[126:127], v[12:13]
	v_pk_mul_f32 v[118:119], v[118:119], v[14:15]
	v_pk_mul_f32 v[120:121], v[120:121], v[100:101]
	ds_write_b128 v178, v[124:127] offset:528
	ds_write_b128 v178, v[118:121] offset:544
	v_mul_f32_e32 v171, v124, v124
	v_mul_f32_e32 v181, v118, v118
	v_fmac_f32_e32 v171, v125, v125
	v_fmac_f32_e32 v181, v119, v119
	v_fmac_f32_e32 v171, v126, v126
	v_fmac_f32_e32 v181, v120, v120
	v_fmac_f32_e32 v171, v127, v127
	v_fmac_f32_e32 v181, v121, v121
	v_add_f32_e32 v171, v171, v181
	s_waitcnt vmcnt(11)
	v_lshlrev_b32_e32 v10, 16, v70
	v_and_b32_e32 v11, 0xffff0000, v70
	v_lshlrev_b32_e32 v12, 16, v71
	v_and_b32_e32 v13, 0xffff0000, v71
	v_lshlrev_b32_e32 v14, 16, v72
	v_and_b32_e32 v15, 0xffff0000, v72
	v_lshlrev_b32_e32 v100, 16, v73
	v_and_b32_e32 v101, 0xffff0000, v73
	v_pk_mul_f32 v[124:125], v[16:17], v[102:103]
	v_pk_mul_f32 v[126:127], v[18:19], v[104:105]
	v_pk_mul_f32 v[118:119], v[20:21], v[106:107]
	v_pk_mul_f32 v[120:121], v[22:23], v[108:109]
	v_pk_fma_f32 v[124:125], v[24:25], v[110:111], v[124:125]
	v_pk_fma_f32 v[126:127], v[26:27], v[112:113], v[126:127]
	v_pk_fma_f32 v[118:119], v[30:31], v[114:115], v[118:119]
	v_pk_fma_f32 v[120:121], v[32:33], v[116:117], v[120:121]
	v_pk_fma_f32 v[124:125], v[34:35], v[2:3], v[124:125]
	v_pk_fma_f32 v[126:127], v[36:37], v[4:5], v[126:127]
	v_pk_fma_f32 v[118:119], v[38:39], v[6:7], v[118:119]
	v_pk_fma_f32 v[120:121], v[40:41], v[8:9], v[120:121]
	v_pk_fma_f32 v[124:125], v[42:43], v[10:11], v[124:125]
	v_pk_fma_f32 v[126:127], v[44:45], v[12:13], v[126:127]
	v_pk_fma_f32 v[118:119], v[46:47], v[14:15], v[118:119]
	v_pk_fma_f32 v[120:121], v[48:49], v[100:101], v[120:121]
	v_mul_f32_e32 v102, 0xbfb8aa3b, v124
	v_mul_f32_e32 v103, 0xbfb8aa3b, v125
	v_mul_f32_e32 v104, 0xbfb8aa3b, v126
	v_mul_f32_e32 v105, 0xbfb8aa3b, v127
	v_mul_f32_e32 v106, 0xbfb8aa3b, v118
	v_mul_f32_e32 v107, 0xbfb8aa3b, v119
	v_mul_f32_e32 v108, 0xbfb8aa3b, v120
	v_mul_f32_e32 v109, 0xbfb8aa3b, v121
	v_exp_f32_e32 v102, v102
	v_exp_f32_e32 v103, v103
	v_exp_f32_e32 v104, v104
	v_exp_f32_e32 v105, v105
	v_exp_f32_e32 v106, v106
	v_exp_f32_e32 v107, v107
	v_exp_f32_e32 v108, v108
	v_exp_f32_e32 v109, v109
	v_add_f32_e32 v102, 1.0, v102
	v_add_f32_e32 v103, 1.0, v103
	v_add_f32_e32 v104, 1.0, v104
	v_add_f32_e32 v105, 1.0, v105
	v_add_f32_e32 v106, 1.0, v106
	v_add_f32_e32 v107, 1.0, v107
	v_add_f32_e32 v108, 1.0, v108
	v_add_f32_e32 v109, 1.0, v109
	v_rcp_f32_e32 v102, v102
	v_rcp_f32_e32 v103, v103
	v_rcp_f32_e32 v104, v104
	v_rcp_f32_e32 v105, v105
	v_rcp_f32_e32 v106, v106
	v_rcp_f32_e32 v107, v107
	v_rcp_f32_e32 v108, v108
	v_rcp_f32_e32 v109, v109
	v_pk_mul_f32 v[124:125], v[124:125], v[102:103]
	v_pk_mul_f32 v[126:127], v[126:127], v[104:105]
	v_pk_mul_f32 v[118:119], v[118:119], v[106:107]
	v_pk_mul_f32 v[120:121], v[120:121], v[108:109]
	ds_write_b128 v178, v[124:127] offset:1056
	ds_write_b128 v178, v[118:121] offset:1072
	v_mul_f32_e32 v172, v124, v124
	v_mul_f32_e32 v181, v118, v118
	v_fmac_f32_e32 v172, v125, v125
	v_fmac_f32_e32 v181, v119, v119
	v_fmac_f32_e32 v172, v126, v126
	v_fmac_f32_e32 v181, v120, v120
	v_fmac_f32_e32 v172, v127, v127
	v_fmac_f32_e32 v181, v121, v121
	v_add_f32_e32 v172, v172, v181
	s_waitcnt vmcnt(10)
	v_lshlrev_b32_e32 v102, 16, v74
	v_and_b32_e32 v103, 0xffff0000, v74
	v_lshlrev_b32_e32 v104, 16, v75
	v_and_b32_e32 v105, 0xffff0000, v75
	v_lshlrev_b32_e32 v106, 16, v76
	v_and_b32_e32 v107, 0xffff0000, v76
	v_lshlrev_b32_e32 v108, 16, v77
	v_and_b32_e32 v109, 0xffff0000, v77
	v_pk_mul_f32 v[124:125], v[16:17], v[110:111]
	v_pk_mul_f32 v[126:127], v[18:19], v[112:113]
	v_pk_mul_f32 v[118:119], v[20:21], v[114:115]
	v_pk_mul_f32 v[120:121], v[22:23], v[116:117]
	v_pk_fma_f32 v[124:125], v[24:25], v[2:3], v[124:125]
	v_pk_fma_f32 v[126:127], v[26:27], v[4:5], v[126:127]
	v_pk_fma_f32 v[118:119], v[30:31], v[6:7], v[118:119]
	v_pk_fma_f32 v[120:121], v[32:33], v[8:9], v[120:121]
	v_pk_fma_f32 v[124:125], v[34:35], v[10:11], v[124:125]
	v_pk_fma_f32 v[126:127], v[36:37], v[12:13], v[126:127]
	v_pk_fma_f32 v[118:119], v[38:39], v[14:15], v[118:119]
	v_pk_fma_f32 v[120:121], v[40:41], v[100:101], v[120:121]
	v_pk_fma_f32 v[124:125], v[42:43], v[102:103], v[124:125]
	v_pk_fma_f32 v[126:127], v[44:45], v[104:105], v[126:127]
	v_pk_fma_f32 v[118:119], v[46:47], v[106:107], v[118:119]
	v_pk_fma_f32 v[120:121], v[48:49], v[108:109], v[120:121]
	v_mul_f32_e32 v110, 0xbfb8aa3b, v124
	v_mul_f32_e32 v111, 0xbfb8aa3b, v125
	v_mul_f32_e32 v112, 0xbfb8aa3b, v126
	v_mul_f32_e32 v113, 0xbfb8aa3b, v127
	v_mul_f32_e32 v114, 0xbfb8aa3b, v118
	v_mul_f32_e32 v115, 0xbfb8aa3b, v119
	v_mul_f32_e32 v116, 0xbfb8aa3b, v120
	v_mul_f32_e32 v117, 0xbfb8aa3b, v121
	v_exp_f32_e32 v110, v110
	v_exp_f32_e32 v111, v111
	v_exp_f32_e32 v112, v112
	v_exp_f32_e32 v113, v113
	v_exp_f32_e32 v114, v114
	v_exp_f32_e32 v115, v115
	v_exp_f32_e32 v116, v116
	v_exp_f32_e32 v117, v117
	v_add_f32_e32 v110, 1.0, v110
	v_add_f32_e32 v111, 1.0, v111
	v_add_f32_e32 v112, 1.0, v112
	v_add_f32_e32 v113, 1.0, v113
	v_add_f32_e32 v114, 1.0, v114
	v_add_f32_e32 v115, 1.0, v115
	v_add_f32_e32 v116, 1.0, v116
	v_add_f32_e32 v117, 1.0, v117
	v_rcp_f32_e32 v110, v110
	v_rcp_f32_e32 v111, v111
	v_rcp_f32_e32 v112, v112
	v_rcp_f32_e32 v113, v113
	v_rcp_f32_e32 v114, v114
	v_rcp_f32_e32 v115, v115
	v_rcp_f32_e32 v116, v116
	v_rcp_f32_e32 v117, v117
	v_pk_mul_f32 v[124:125], v[124:125], v[110:111]
	v_pk_mul_f32 v[126:127], v[126:127], v[112:113]
	v_pk_mul_f32 v[118:119], v[118:119], v[114:115]
	v_pk_mul_f32 v[120:121], v[120:121], v[116:117]
	ds_write_b128 v178, v[124:127] offset:1584
	ds_write_b128 v178, v[118:121] offset:1600
	v_mul_f32_e32 v173, v124, v124
	v_mul_f32_e32 v181, v118, v118
	v_fmac_f32_e32 v173, v125, v125
	v_fmac_f32_e32 v181, v119, v119
	v_fmac_f32_e32 v173, v126, v126
	v_fmac_f32_e32 v181, v120, v120
	v_fmac_f32_e32 v173, v127, v127
	v_fmac_f32_e32 v181, v121, v121
	v_add_f32_e32 v173, v173, v181
	s_waitcnt vmcnt(9)
	v_lshlrev_b32_e32 v110, 16, v78
	v_and_b32_e32 v111, 0xffff0000, v78
	v_lshlrev_b32_e32 v112, 16, v79
	v_and_b32_e32 v113, 0xffff0000, v79
	v_lshlrev_b32_e32 v114, 16, v80
	v_and_b32_e32 v115, 0xffff0000, v80
	v_lshlrev_b32_e32 v116, 16, v81
	v_and_b32_e32 v117, 0xffff0000, v81
	v_pk_mul_f32 v[124:125], v[16:17], v[2:3]
	v_pk_mul_f32 v[126:127], v[18:19], v[4:5]
	v_pk_mul_f32 v[118:119], v[20:21], v[6:7]
	v_pk_mul_f32 v[120:121], v[22:23], v[8:9]
	v_pk_fma_f32 v[124:125], v[24:25], v[10:11], v[124:125]
	v_pk_fma_f32 v[126:127], v[26:27], v[12:13], v[126:127]
	v_pk_fma_f32 v[118:119], v[30:31], v[14:15], v[118:119]
	v_pk_fma_f32 v[120:121], v[32:33], v[100:101], v[120:121]
	v_pk_fma_f32 v[124:125], v[34:35], v[102:103], v[124:125]
	v_pk_fma_f32 v[126:127], v[36:37], v[104:105], v[126:127]
	v_pk_fma_f32 v[118:119], v[38:39], v[106:107], v[118:119]
	v_pk_fma_f32 v[120:121], v[40:41], v[108:109], v[120:121]
	v_pk_fma_f32 v[124:125], v[42:43], v[110:111], v[124:125]
	v_pk_fma_f32 v[126:127], v[44:45], v[112:113], v[126:127]
	v_pk_fma_f32 v[118:119], v[46:47], v[114:115], v[118:119]
	v_pk_fma_f32 v[120:121], v[48:49], v[116:117], v[120:121]
	v_mul_f32_e32 v2, 0xbfb8aa3b, v124
	v_mul_f32_e32 v3, 0xbfb8aa3b, v125
	v_mul_f32_e32 v4, 0xbfb8aa3b, v126
	v_mul_f32_e32 v5, 0xbfb8aa3b, v127
	v_mul_f32_e32 v6, 0xbfb8aa3b, v118
	v_mul_f32_e32 v7, 0xbfb8aa3b, v119
	v_mul_f32_e32 v8, 0xbfb8aa3b, v120
	v_mul_f32_e32 v9, 0xbfb8aa3b, v121
	v_exp_f32_e32 v2, v2
	v_exp_f32_e32 v3, v3
	v_exp_f32_e32 v4, v4
	v_exp_f32_e32 v5, v5
	v_exp_f32_e32 v6, v6
	v_exp_f32_e32 v7, v7
	v_exp_f32_e32 v8, v8
	v_exp_f32_e32 v9, v9
	v_add_f32_e32 v2, 1.0, v2
	v_add_f32_e32 v3, 1.0, v3
	v_add_f32_e32 v4, 1.0, v4
	v_add_f32_e32 v5, 1.0, v5
	v_add_f32_e32 v6, 1.0, v6
	v_add_f32_e32 v7, 1.0, v7
	v_add_f32_e32 v8, 1.0, v8
	v_add_f32_e32 v9, 1.0, v9
	v_rcp_f32_e32 v2, v2
	v_rcp_f32_e32 v3, v3
	v_rcp_f32_e32 v4, v4
	v_rcp_f32_e32 v5, v5
	v_rcp_f32_e32 v6, v6
	v_rcp_f32_e32 v7, v7
	v_rcp_f32_e32 v8, v8
	v_rcp_f32_e32 v9, v9
	v_pk_mul_f32 v[124:125], v[124:125], v[2:3]
	v_pk_mul_f32 v[126:127], v[126:127], v[4:5]
	v_pk_mul_f32 v[118:119], v[118:119], v[6:7]
	v_pk_mul_f32 v[120:121], v[120:121], v[8:9]
	ds_write_b128 v178, v[124:127] offset:2112
	ds_write_b128 v178, v[118:121] offset:2128
	v_mul_f32_e32 v174, v124, v124
	v_mul_f32_e32 v181, v118, v118
	v_fmac_f32_e32 v174, v125, v125
	v_fmac_f32_e32 v181, v119, v119
	v_fmac_f32_e32 v174, v126, v126
	v_fmac_f32_e32 v181, v120, v120
	v_fmac_f32_e32 v174, v127, v127
	v_fmac_f32_e32 v181, v121, v121
	v_add_f32_e32 v174, v174, v181
	s_waitcnt vmcnt(8)
	v_lshlrev_b32_e32 v2, 16, v88
	v_and_b32_e32 v3, 0xffff0000, v88
	v_lshlrev_b32_e32 v4, 16, v89
	v_and_b32_e32 v5, 0xffff0000, v89
	v_lshlrev_b32_e32 v6, 16, v90
	v_and_b32_e32 v7, 0xffff0000, v90
	v_lshlrev_b32_e32 v8, 16, v91
	v_and_b32_e32 v9, 0xffff0000, v91
	v_pk_mul_f32 v[124:125], v[16:17], v[10:11]
	v_pk_mul_f32 v[126:127], v[18:19], v[12:13]
	v_pk_mul_f32 v[118:119], v[20:21], v[14:15]
	v_pk_mul_f32 v[120:121], v[22:23], v[100:101]
	v_pk_fma_f32 v[124:125], v[24:25], v[102:103], v[124:125]
	v_pk_fma_f32 v[126:127], v[26:27], v[104:105], v[126:127]
	v_pk_fma_f32 v[118:119], v[30:31], v[106:107], v[118:119]
	v_pk_fma_f32 v[120:121], v[32:33], v[108:109], v[120:121]
	v_pk_fma_f32 v[124:125], v[34:35], v[110:111], v[124:125]
	v_pk_fma_f32 v[126:127], v[36:37], v[112:113], v[126:127]
	v_pk_fma_f32 v[118:119], v[38:39], v[114:115], v[118:119]
	v_pk_fma_f32 v[120:121], v[40:41], v[116:117], v[120:121]
	v_pk_fma_f32 v[124:125], v[42:43], v[2:3], v[124:125]
	v_pk_fma_f32 v[126:127], v[44:45], v[4:5], v[126:127]
	v_pk_fma_f32 v[118:119], v[46:47], v[6:7], v[118:119]
	v_pk_fma_f32 v[120:121], v[48:49], v[8:9], v[120:121]
	v_mul_f32_e32 v10, 0xbfb8aa3b, v124
	v_mul_f32_e32 v11, 0xbfb8aa3b, v125
	v_mul_f32_e32 v12, 0xbfb8aa3b, v126
	v_mul_f32_e32 v13, 0xbfb8aa3b, v127
	v_mul_f32_e32 v14, 0xbfb8aa3b, v118
	v_mul_f32_e32 v15, 0xbfb8aa3b, v119
	v_mul_f32_e32 v100, 0xbfb8aa3b, v120
	v_mul_f32_e32 v101, 0xbfb8aa3b, v121
	v_exp_f32_e32 v10, v10
	v_exp_f32_e32 v11, v11
	v_exp_f32_e32 v12, v12
	v_exp_f32_e32 v13, v13
	v_exp_f32_e32 v14, v14
	v_exp_f32_e32 v15, v15
	v_exp_f32_e32 v100, v100
	v_exp_f32_e32 v101, v101
	v_add_f32_e32 v10, 1.0, v10
	v_add_f32_e32 v11, 1.0, v11
	v_add_f32_e32 v12, 1.0, v12
	v_add_f32_e32 v13, 1.0, v13
	v_add_f32_e32 v14, 1.0, v14
	v_add_f32_e32 v15, 1.0, v15
	v_add_f32_e32 v100, 1.0, v100
	v_add_f32_e32 v101, 1.0, v101
	v_rcp_f32_e32 v10, v10
	v_rcp_f32_e32 v11, v11
	v_rcp_f32_e32 v12, v12
	v_rcp_f32_e32 v13, v13
	v_rcp_f32_e32 v14, v14
	v_rcp_f32_e32 v15, v15
	v_rcp_f32_e32 v100, v100
	v_rcp_f32_e32 v101, v101
	v_pk_mul_f32 v[124:125], v[124:125], v[10:11]
	v_pk_mul_f32 v[126:127], v[126:127], v[12:13]
	v_pk_mul_f32 v[118:119], v[118:119], v[14:15]
	v_pk_mul_f32 v[120:121], v[120:121], v[100:101]
	ds_write_b128 v178, v[124:127] offset:2640
	ds_write_b128 v178, v[118:121] offset:2656
	v_mul_f32_e32 v175, v124, v124
	v_mul_f32_e32 v181, v118, v118
	v_fmac_f32_e32 v175, v125, v125
	v_fmac_f32_e32 v181, v119, v119
	v_fmac_f32_e32 v175, v126, v126
	v_fmac_f32_e32 v181, v120, v120
	v_fmac_f32_e32 v175, v127, v127
	v_fmac_f32_e32 v181, v121, v121
	v_add_f32_e32 v175, v175, v181
	s_waitcnt vmcnt(7)
	v_lshlrev_b32_e32 v10, 16, v92
	v_and_b32_e32 v11, 0xffff0000, v92
	v_lshlrev_b32_e32 v12, 16, v93
	v_and_b32_e32 v13, 0xffff0000, v93
	v_lshlrev_b32_e32 v14, 16, v94
	v_and_b32_e32 v15, 0xffff0000, v94
	v_lshlrev_b32_e32 v100, 16, v95
	v_and_b32_e32 v101, 0xffff0000, v95
	v_pk_mul_f32 v[124:125], v[16:17], v[102:103]
	v_pk_mul_f32 v[126:127], v[18:19], v[104:105]
	v_pk_mul_f32 v[118:119], v[20:21], v[106:107]
	v_pk_mul_f32 v[120:121], v[22:23], v[108:109]
	v_pk_fma_f32 v[124:125], v[24:25], v[110:111], v[124:125]
	v_pk_fma_f32 v[126:127], v[26:27], v[112:113], v[126:127]
	v_pk_fma_f32 v[118:119], v[30:31], v[114:115], v[118:119]
	v_pk_fma_f32 v[120:121], v[32:33], v[116:117], v[120:121]
	v_pk_fma_f32 v[124:125], v[34:35], v[2:3], v[124:125]
	v_pk_fma_f32 v[126:127], v[36:37], v[4:5], v[126:127]
	v_pk_fma_f32 v[118:119], v[38:39], v[6:7], v[118:119]
	v_pk_fma_f32 v[120:121], v[40:41], v[8:9], v[120:121]
	v_pk_fma_f32 v[124:125], v[42:43], v[10:11], v[124:125]
	v_pk_fma_f32 v[126:127], v[44:45], v[12:13], v[126:127]
	v_pk_fma_f32 v[118:119], v[46:47], v[14:15], v[118:119]
	v_pk_fma_f32 v[120:121], v[48:49], v[100:101], v[120:121]
	v_mul_f32_e32 v102, 0xbfb8aa3b, v124
	v_mul_f32_e32 v103, 0xbfb8aa3b, v125
	v_mul_f32_e32 v104, 0xbfb8aa3b, v126
	v_mul_f32_e32 v105, 0xbfb8aa3b, v127
	v_mul_f32_e32 v106, 0xbfb8aa3b, v118
	v_mul_f32_e32 v107, 0xbfb8aa3b, v119
	v_mul_f32_e32 v108, 0xbfb8aa3b, v120
	v_mul_f32_e32 v109, 0xbfb8aa3b, v121
	v_exp_f32_e32 v102, v102
	v_exp_f32_e32 v103, v103
	v_exp_f32_e32 v104, v104
	v_exp_f32_e32 v105, v105
	v_exp_f32_e32 v106, v106
	v_exp_f32_e32 v107, v107
	v_exp_f32_e32 v108, v108
	v_exp_f32_e32 v109, v109
	v_add_f32_e32 v102, 1.0, v102
	v_add_f32_e32 v103, 1.0, v103
	v_add_f32_e32 v104, 1.0, v104
	v_add_f32_e32 v105, 1.0, v105
	v_add_f32_e32 v106, 1.0, v106
	v_add_f32_e32 v107, 1.0, v107
	v_add_f32_e32 v108, 1.0, v108
	v_add_f32_e32 v109, 1.0, v109
	v_rcp_f32_e32 v102, v102
	v_rcp_f32_e32 v103, v103
	v_rcp_f32_e32 v104, v104
	v_rcp_f32_e32 v105, v105
	v_rcp_f32_e32 v106, v106
	v_rcp_f32_e32 v107, v107
	v_rcp_f32_e32 v108, v108
	v_rcp_f32_e32 v109, v109
	v_pk_mul_f32 v[124:125], v[124:125], v[102:103]
	v_pk_mul_f32 v[126:127], v[126:127], v[104:105]
	v_pk_mul_f32 v[118:119], v[118:119], v[106:107]
	v_pk_mul_f32 v[120:121], v[120:121], v[108:109]
	ds_write_b128 v178, v[124:127] offset:3168
	ds_write_b128 v178, v[118:121] offset:3184
	v_mul_f32_e32 v176, v124, v124
	v_mul_f32_e32 v181, v118, v118
	v_fmac_f32_e32 v176, v125, v125
	v_fmac_f32_e32 v181, v119, v119
	v_fmac_f32_e32 v176, v126, v126
	v_fmac_f32_e32 v181, v120, v120
	v_fmac_f32_e32 v176, v127, v127
	v_fmac_f32_e32 v181, v121, v121
	v_add_f32_e32 v176, v176, v181
	s_waitcnt vmcnt(6)
	v_lshlrev_b32_e32 v102, 16, v96
	v_and_b32_e32 v103, 0xffff0000, v96
	v_lshlrev_b32_e32 v104, 16, v97
	v_and_b32_e32 v105, 0xffff0000, v97
	v_lshlrev_b32_e32 v106, 16, v98
	v_and_b32_e32 v107, 0xffff0000, v98
	v_lshlrev_b32_e32 v108, 16, v99
	v_and_b32_e32 v109, 0xffff0000, v99
	v_pk_mul_f32 v[124:125], v[16:17], v[110:111]
	v_pk_mul_f32 v[126:127], v[18:19], v[112:113]
	v_pk_mul_f32 v[118:119], v[20:21], v[114:115]
	v_pk_mul_f32 v[120:121], v[22:23], v[116:117]
	v_pk_fma_f32 v[124:125], v[24:25], v[2:3], v[124:125]
	v_pk_fma_f32 v[126:127], v[26:27], v[4:5], v[126:127]
	v_pk_fma_f32 v[118:119], v[30:31], v[6:7], v[118:119]
	v_pk_fma_f32 v[120:121], v[32:33], v[8:9], v[120:121]
	v_pk_fma_f32 v[124:125], v[34:35], v[10:11], v[124:125]
	v_pk_fma_f32 v[126:127], v[36:37], v[12:13], v[126:127]
	v_pk_fma_f32 v[118:119], v[38:39], v[14:15], v[118:119]
	v_pk_fma_f32 v[120:121], v[40:41], v[100:101], v[120:121]
	v_pk_fma_f32 v[124:125], v[42:43], v[102:103], v[124:125]
	v_pk_fma_f32 v[126:127], v[44:45], v[104:105], v[126:127]
	v_pk_fma_f32 v[118:119], v[46:47], v[106:107], v[118:119]
	v_pk_fma_f32 v[120:121], v[48:49], v[108:109], v[120:121]
	v_mul_f32_e32 v110, 0xbfb8aa3b, v124
	v_mul_f32_e32 v111, 0xbfb8aa3b, v125
	v_mul_f32_e32 v112, 0xbfb8aa3b, v126
	v_mul_f32_e32 v113, 0xbfb8aa3b, v127
	v_mul_f32_e32 v114, 0xbfb8aa3b, v118
	v_mul_f32_e32 v115, 0xbfb8aa3b, v119
	v_mul_f32_e32 v116, 0xbfb8aa3b, v120
	v_mul_f32_e32 v117, 0xbfb8aa3b, v121
	v_exp_f32_e32 v110, v110
	v_exp_f32_e32 v111, v111
	v_exp_f32_e32 v112, v112
	v_exp_f32_e32 v113, v113
	v_exp_f32_e32 v114, v114
	v_exp_f32_e32 v115, v115
	v_exp_f32_e32 v116, v116
	v_exp_f32_e32 v117, v117
	v_add_f32_e32 v110, 1.0, v110
	v_add_f32_e32 v111, 1.0, v111
	v_add_f32_e32 v112, 1.0, v112
	v_add_f32_e32 v113, 1.0, v113
	v_add_f32_e32 v114, 1.0, v114
	v_add_f32_e32 v115, 1.0, v115
	v_add_f32_e32 v116, 1.0, v116
	v_add_f32_e32 v117, 1.0, v117
	v_rcp_f32_e32 v110, v110
	v_rcp_f32_e32 v111, v111
	v_rcp_f32_e32 v112, v112
	v_rcp_f32_e32 v113, v113
	v_rcp_f32_e32 v114, v114
	v_rcp_f32_e32 v115, v115
	v_rcp_f32_e32 v116, v116
	v_rcp_f32_e32 v117, v117
	v_pk_mul_f32 v[124:125], v[124:125], v[110:111]
	v_pk_mul_f32 v[126:127], v[126:127], v[112:113]
	v_pk_mul_f32 v[118:119], v[118:119], v[114:115]
	v_pk_mul_f32 v[120:121], v[120:121], v[116:117]
	ds_write_b128 v178, v[124:127] offset:3696
	ds_write_b128 v178, v[118:121] offset:3712
	v_mul_f32_e32 v177, v124, v124
	v_mul_f32_e32 v181, v118, v118
	v_fmac_f32_e32 v177, v125, v125
	v_fmac_f32_e32 v181, v119, v119
	v_fmac_f32_e32 v177, v126, v126
	v_fmac_f32_e32 v181, v120, v120
	v_fmac_f32_e32 v177, v127, v127
	v_fmac_f32_e32 v181, v121, v121
	v_add_f32_e32 v177, v177, v181
	v_add_f32_dpp v170, v170, v170 quad_perm:[1,0,3,2] row_mask:0xf bank_mask:0xf
	v_add_f32_dpp v171, v171, v171 quad_perm:[1,0,3,2] row_mask:0xf bank_mask:0xf
	v_add_f32_dpp v172, v172, v172 quad_perm:[1,0,3,2] row_mask:0xf bank_mask:0xf
	v_add_f32_dpp v173, v173, v173 quad_perm:[1,0,3,2] row_mask:0xf bank_mask:0xf
	v_add_f32_dpp v174, v174, v174 quad_perm:[1,0,3,2] row_mask:0xf bank_mask:0xf
	v_add_f32_dpp v175, v175, v175 quad_perm:[1,0,3,2] row_mask:0xf bank_mask:0xf
	v_add_f32_dpp v176, v176, v176 quad_perm:[1,0,3,2] row_mask:0xf bank_mask:0xf
	v_add_f32_dpp v177, v177, v177 quad_perm:[1,0,3,2] row_mask:0xf bank_mask:0xf
	v_add_f32_dpp v170, v170, v170 quad_perm:[2,3,0,1] row_mask:0xf bank_mask:0xf
	v_add_f32_dpp v171, v171, v171 quad_perm:[2,3,0,1] row_mask:0xf bank_mask:0xf
	v_add_f32_dpp v172, v172, v172 quad_perm:[2,3,0,1] row_mask:0xf bank_mask:0xf
	v_add_f32_dpp v173, v173, v173 quad_perm:[2,3,0,1] row_mask:0xf bank_mask:0xf
	v_add_f32_dpp v174, v174, v174 quad_perm:[2,3,0,1] row_mask:0xf bank_mask:0xf
	v_add_f32_dpp v175, v175, v175 quad_perm:[2,3,0,1] row_mask:0xf bank_mask:0xf
	v_add_f32_dpp v176, v176, v176 quad_perm:[2,3,0,1] row_mask:0xf bank_mask:0xf
	v_add_f32_dpp v177, v177, v177 quad_perm:[2,3,0,1] row_mask:0xf bank_mask:0xf
	v_add_f32_dpp v170, v170, v170 row_half_mirror row_mask:0xf bank_mask:0xf
	v_add_f32_dpp v171, v171, v171 row_half_mirror row_mask:0xf bank_mask:0xf
	v_add_f32_dpp v172, v172, v172 row_half_mirror row_mask:0xf bank_mask:0xf
	v_add_f32_dpp v173, v173, v173 row_half_mirror row_mask:0xf bank_mask:0xf
	v_add_f32_dpp v174, v174, v174 row_half_mirror row_mask:0xf bank_mask:0xf
	v_add_f32_dpp v175, v175, v175 row_half_mirror row_mask:0xf bank_mask:0xf
	v_add_f32_dpp v176, v176, v176 row_half_mirror row_mask:0xf bank_mask:0xf
	v_add_f32_dpp v177, v177, v177 row_half_mirror row_mask:0xf bank_mask:0xf
	v_add_f32_dpp v170, v170, v170 row_mirror row_mask:0xf bank_mask:0xf
	v_add_f32_dpp v171, v171, v171 row_mirror row_mask:0xf bank_mask:0xf
	v_add_f32_dpp v172, v172, v172 row_mirror row_mask:0xf bank_mask:0xf
	v_add_f32_dpp v173, v173, v173 row_mirror row_mask:0xf bank_mask:0xf
	v_add_f32_dpp v174, v174, v174 row_mirror row_mask:0xf bank_mask:0xf
	v_add_f32_dpp v175, v175, v175 row_mirror row_mask:0xf bank_mask:0xf
	v_add_f32_dpp v176, v176, v176 row_mirror row_mask:0xf bank_mask:0xf
	v_add_f32_dpp v177, v177, v177 row_mirror row_mask:0xf bank_mask:0xf
	v_cmp_eq_u32_e32 vcc, 0, v128
	s_nop 1
	s_and_saveexec_b64 s[28:29], vcc
	ds_write_b32 v179, v170 offset:0
	ds_write_b32 v179, v171 offset:4
	ds_write_b32 v179, v172 offset:8
	ds_write_b32 v179, v173 offset:12
	ds_write_b32 v179, v174 offset:16
	ds_write_b32 v179, v175 offset:20
	ds_write_b32 v179, v176 offset:24
	ds_write_b32 v179, v177 offset:28
	s_mov_b64 exec, s[28:29]
	s_branch .Lcv_done
.Lcv_vwaves:
	s_lshr_b32 s28, s88, 5
	v_lshrrev_b32_e32 v181, 4, v160
	s_sub_u32 s29, s28, 4
	s_lshl_b32 s29, s29, 4
	v_lshl_add_u32 v180, v181, 2, s29
	s_mov_b32 s55, 2
	v_and_b32_e32 v128, 15, v160
	s_mul_i32 s28, s55, 0x8400
	v_lshlrev_b32_e32 v178, 9, v180
	v_lshl_add_u32 v178, v180, 4, v178
	v_lshl_add_u32 v178, v128, 5, v178
	v_add3_u32 v178, v178, v234, s28
	s_waitcnt vmcnt(10)
	s_cmp_lg_u32 s37, 0
	s_cbranch_scc1 .Lcv_nz_b
	v_cmp_eq_u32_e32 vcc, 0, v180
	s_nop 1
	v_cndmask_b32_e64 v50, v50, 0, vcc
	v_cndmask_b32_e64 v51, v51, 0, vcc
	v_cndmask_b32_e64 v52, v52, 0, vcc
	v_cndmask_b32_e64 v53, v53, 0, vcc
	v_cndmask_b32_e64 v54, v54, 0, vcc
	v_cndmask_b32_e64 v55, v55, 0, vcc
	v_cndmask_b32_e64 v56, v56, 0, vcc
	v_cndmask_b32_e64 v57, v57, 0, vcc
	v_cndmask_b32_e64 v58, v58, 0, vcc
	v_cndmask_b32_e64 v59, v59, 0, vcc
	v_cndmask_b32_e64 v60, v60, 0, vcc
	v_cndmask_b32_e64 v61, v61, 0, vcc
.Lcv_nz_b:
	v_lshlrev_b32_e32 v2, 16, v50
	v_and_b32_e32 v3, 0xffff0000, v50
	v_lshlrev_b32_e32 v4, 16, v51
	v_and_b32_e32 v5, 0xffff0000, v51
	v_lshlrev_b32_e32 v6, 16, v52
	v_and_b32_e32 v7, 0xffff0000, v52
	v_lshlrev_b32_e32 v8, 16, v53
	v_and_b32_e32 v9, 0xffff0000, v53
	v_lshlrev_b32_e32 v10, 16, v54
	v_and_b32_e32 v11, 0xffff0000, v54
	v_lshlrev_b32_e32 v12, 16, v55
	v_and_b32_e32 v13, 0xffff0000, v55
	v_lshlrev_b32_e32 v14, 16, v56
	v_and_b32_e32 v15, 0xffff0000, v56
	v_lshlrev_b32_e32 v100, 16, v57
	v_and_b32_e32 v101, 0xffff0000, v57
	v_lshlrev_b32_e32 v102, 16, v58
	v_and_b32_e32 v103, 0xffff0000, v58
	v_lshlrev_b32_e32 v104, 16, v59
	v_and_b32_e32 v105, 0xffff0000, v59
	v_lshlrev_b32_e32 v106, 16, v60
	v_and_b32_e32 v107, 0xffff0000, v60
	v_lshlrev_b32_e32 v108, 16, v61
	v_and_b32_e32 v109, 0xffff0000, v61
	s_waitcnt vmcnt(9)
	v_lshlrev_b32_e32 v110, 16, v62
	v_and_b32_e32 v111, 0xffff0000, v62
	v_lshlrev_b32_e32 v112, 16, v63
	v_and_b32_e32 v113, 0xffff0000, v63
	v_lshlrev_b32_e32 v114, 16, v64
	v_and_b32_e32 v115, 0xffff0000, v64
	v_lshlrev_b32_e32 v116, 16, v65
	v_and_b32_e32 v117, 0xffff0000, v65
	v_pk_mul_f32 v[124:125], v[16:17], v[2:3]
	v_pk_mul_f32 v[126:127], v[18:19], v[4:5]
	v_pk_mul_f32 v[118:119], v[20:21], v[6:7]
	v_pk_mul_f32 v[120:121], v[22:23], v[8:9]
	v_pk_fma_f32 v[124:125], v[24:25], v[10:11], v[124:125]
	v_pk_fma_f32 v[126:127], v[26:27], v[12:13], v[126:127]
	v_pk_fma_f32 v[118:119], v[30:31], v[14:15], v[118:119]
	v_pk_fma_f32 v[120:121], v[32:33], v[100:101], v[120:121]
	v_pk_fma_f32 v[124:125], v[34:35], v[102:103], v[124:125]
	v_pk_fma_f32 v[126:127], v[36:37], v[104:105], v[126:127]
	v_pk_fma_f32 v[118:119], v[38:39], v[106:107], v[118:119]
	v_pk_fma_f32 v[120:121], v[40:41], v[108:109], v[120:121]
	v_pk_fma_f32 v[124:125], v[42:43], v[110:111], v[124:125]
	v_pk_fma_f32 v[126:127], v[44:45], v[112:113], v[126:127]
	v_pk_fma_f32 v[118:119], v[46:47], v[114:115], v[118:119]
	v_pk_fma_f32 v[120:121], v[48:49], v[116:117], v[120:121]
	v_mul_f32_e32 v2, 0xbfb8aa3b, v124
	v_mul_f32_e32 v3, 0xbfb8aa3b, v125
	v_mul_f32_e32 v4, 0xbfb8aa3b, v126
	v_mul_f32_e32 v5, 0xbfb8aa3b, v127
	v_mul_f32_e32 v6, 0xbfb8aa3b, v118
	v_mul_f32_e32 v7, 0xbfb8aa3b, v119
	v_mul_f32_e32 v8, 0xbfb8aa3b, v120
	v_mul_f32_e32 v9, 0xbfb8aa3b, v121
	v_exp_f32_e32 v2, v2
	v_exp_f32_e32 v3, v3
	v_exp_f32_e32 v4, v4
	v_exp_f32_e32 v5, v5
	v_exp_f32_e32 v6, v6
	v_exp_f32_e32 v7, v7
	v_exp_f32_e32 v8, v8
	v_exp_f32_e32 v9, v9
	v_add_f32_e32 v2, 1.0, v2
	v_add_f32_e32 v3, 1.0, v3
	v_add_f32_e32 v4, 1.0, v4
	v_add_f32_e32 v5, 1.0, v5
	v_add_f32_e32 v6, 1.0, v6
	v_add_f32_e32 v7, 1.0, v7
	v_add_f32_e32 v8, 1.0, v8
	v_add_f32_e32 v9, 1.0, v9
	v_rcp_f32_e32 v2, v2
	v_rcp_f32_e32 v3, v3
	v_rcp_f32_e32 v4, v4
	v_rcp_f32_e32 v5, v5
	v_rcp_f32_e32 v6, v6
	v_rcp_f32_e32 v7, v7
	v_rcp_f32_e32 v8, v8
	v_rcp_f32_e32 v9, v9
	v_pk_mul_f32 v[124:125], v[124:125], v[2:3]
	v_pk_mul_f32 v[126:127], v[126:127], v[4:5]
	v_pk_mul_f32 v[118:119], v[118:119], v[6:7]
	v_pk_mul_f32 v[120:121], v[120:121], v[8:9]
	ds_write_b128 v178, v[124:127] offset:0
	ds_write_b128 v178, v[118:121] offset:16
	s_waitcnt vmcnt(8)
	v_lshlrev_b32_e32 v2, 16, v66
	v_and_b32_e32 v3, 0xffff0000, v66
	v_lshlrev_b32_e32 v4, 16, v67
	v_and_b32_e32 v5, 0xffff0000, v67
	v_lshlrev_b32_e32 v6, 16, v68
	v_and_b32_e32 v7, 0xffff0000, v68
	v_lshlrev_b32_e32 v8, 16, v69
	v_and_b32_e32 v9, 0xffff0000, v69
	v_pk_mul_f32 v[124:125], v[16:17], v[10:11]
	v_pk_mul_f32 v[126:127], v[18:19], v[12:13]
	v_pk_mul_f32 v[118:119], v[20:21], v[14:15]
	v_pk_mul_f32 v[120:121], v[22:23], v[100:101]
	v_pk_fma_f32 v[124:125], v[24:25], v[102:103], v[124:125]
	v_pk_fma_f32 v[126:127], v[26:27], v[104:105], v[126:127]
	v_pk_fma_f32 v[118:119], v[30:31], v[106:107], v[118:119]
	v_pk_fma_f32 v[120:121], v[32:33], v[108:109], v[120:121]
	v_pk_fma_f32 v[124:125], v[34:35], v[110:111], v[124:125]
	v_pk_fma_f32 v[126:127], v[36:37], v[112:113], v[126:127]
	v_pk_fma_f32 v[118:119], v[38:39], v[114:115], v[118:119]
	v_pk_fma_f32 v[120:121], v[40:41], v[116:117], v[120:121]
	v_pk_fma_f32 v[124:125], v[42:43], v[2:3], v[124:125]
	v_pk_fma_f32 v[126:127], v[44:45], v[4:5], v[126:127]
	v_pk_fma_f32 v[118:119], v[46:47], v[6:7], v[118:119]
	v_pk_fma_f32 v[120:121], v[48:49], v[8:9], v[120:121]
	v_mul_f32_e32 v10, 0xbfb8aa3b, v124
	v_mul_f32_e32 v11, 0xbfb8aa3b, v125
	v_mul_f32_e32 v12, 0xbfb8aa3b, v126
	v_mul_f32_e32 v13, 0xbfb8aa3b, v127
	v_mul_f32_e32 v14, 0xbfb8aa3b, v118
	v_mul_f32_e32 v15, 0xbfb8aa3b, v119
	v_mul_f32_e32 v100, 0xbfb8aa3b, v120
	v_mul_f32_e32 v101, 0xbfb8aa3b, v121
	v_exp_f32_e32 v10, v10
	v_exp_f32_e32 v11, v11
	v_exp_f32_e32 v12, v12
	v_exp_f32_e32 v13, v13
	v_exp_f32_e32 v14, v14
	v_exp_f32_e32 v15, v15
	v_exp_f32_e32 v100, v100
	v_exp_f32_e32 v101, v101
	v_add_f32_e32 v10, 1.0, v10
	v_add_f32_e32 v11, 1.0, v11
	v_add_f32_e32 v12, 1.0, v12
	v_add_f32_e32 v13, 1.0, v13
	v_add_f32_e32 v14, 1.0, v14
	v_add_f32_e32 v15, 1.0, v15
	v_add_f32_e32 v100, 1.0, v100
	v_add_f32_e32 v101, 1.0, v101
	v_rcp_f32_e32 v10, v10
	v_rcp_f32_e32 v11, v11
	v_rcp_f32_e32 v12, v12
	v_rcp_f32_e32 v13, v13
	v_rcp_f32_e32 v14, v14
	v_rcp_f32_e32 v15, v15
	v_rcp_f32_e32 v100, v100
	v_rcp_f32_e32 v101, v101
	v_pk_mul_f32 v[124:125], v[124:125], v[10:11]
	v_pk_mul_f32 v[126:127], v[126:127], v[12:13]
	v_pk_mul_f32 v[118:119], v[118:119], v[14:15]
	v_pk_mul_f32 v[120:121], v[120:121], v[100:101]
	ds_write_b128 v178, v[124:127] offset:528
	ds_write_b128 v178, v[118:121] offset:544
	s_waitcnt vmcnt(7)
	v_lshlrev_b32_e32 v10, 16, v70
	v_and_b32_e32 v11, 0xffff0000, v70
	v_lshlrev_b32_e32 v12, 16, v71
	v_and_b32_e32 v13, 0xffff0000, v71
	v_lshlrev_b32_e32 v14, 16, v72
	v_and_b32_e32 v15, 0xffff0000, v72
	v_lshlrev_b32_e32 v100, 16, v73
	v_and_b32_e32 v101, 0xffff0000, v73
	v_pk_mul_f32 v[124:125], v[16:17], v[102:103]
	v_pk_mul_f32 v[126:127], v[18:19], v[104:105]
	v_pk_mul_f32 v[118:119], v[20:21], v[106:107]
	v_pk_mul_f32 v[120:121], v[22:23], v[108:109]
	v_pk_fma_f32 v[124:125], v[24:25], v[110:111], v[124:125]
	v_pk_fma_f32 v[126:127], v[26:27], v[112:113], v[126:127]
	v_pk_fma_f32 v[118:119], v[30:31], v[114:115], v[118:119]
	v_pk_fma_f32 v[120:121], v[32:33], v[116:117], v[120:121]
	v_pk_fma_f32 v[124:125], v[34:35], v[2:3], v[124:125]
	v_pk_fma_f32 v[126:127], v[36:37], v[4:5], v[126:127]
	v_pk_fma_f32 v[118:119], v[38:39], v[6:7], v[118:119]
	v_pk_fma_f32 v[120:121], v[40:41], v[8:9], v[120:121]
	v_pk_fma_f32 v[124:125], v[42:43], v[10:11], v[124:125]
	v_pk_fma_f32 v[126:127], v[44:45], v[12:13], v[126:127]
	v_pk_fma_f32 v[118:119], v[46:47], v[14:15], v[118:119]
	v_pk_fma_f32 v[120:121], v[48:49], v[100:101], v[120:121]
	v_mul_f32_e32 v102, 0xbfb8aa3b, v124
	v_mul_f32_e32 v103, 0xbfb8aa3b, v125
	v_mul_f32_e32 v104, 0xbfb8aa3b, v126
	v_mul_f32_e32 v105, 0xbfb8aa3b, v127
	v_mul_f32_e32 v106, 0xbfb8aa3b, v118
	v_mul_f32_e32 v107, 0xbfb8aa3b, v119
	v_mul_f32_e32 v108, 0xbfb8aa3b, v120
	v_mul_f32_e32 v109, 0xbfb8aa3b, v121
	v_exp_f32_e32 v102, v102
	v_exp_f32_e32 v103, v103
	v_exp_f32_e32 v104, v104
	v_exp_f32_e32 v105, v105
	v_exp_f32_e32 v106, v106
	v_exp_f32_e32 v107, v107
	v_exp_f32_e32 v108, v108
	v_exp_f32_e32 v109, v109
	v_add_f32_e32 v102, 1.0, v102
	v_add_f32_e32 v103, 1.0, v103
	v_add_f32_e32 v104, 1.0, v104
	v_add_f32_e32 v105, 1.0, v105
	v_add_f32_e32 v106, 1.0, v106
	v_add_f32_e32 v107, 1.0, v107
	v_add_f32_e32 v108, 1.0, v108
	v_add_f32_e32 v109, 1.0, v109
	v_rcp_f32_e32 v102, v102
	v_rcp_f32_e32 v103, v103
	v_rcp_f32_e32 v104, v104
	v_rcp_f32_e32 v105, v105
	v_rcp_f32_e32 v106, v106
	v_rcp_f32_e32 v107, v107
	v_rcp_f32_e32 v108, v108
	v_rcp_f32_e32 v109, v109
	v_pk_mul_f32 v[124:125], v[124:125], v[102:103]
	v_pk_mul_f32 v[126:127], v[126:127], v[104:105]
	v_pk_mul_f32 v[118:119], v[118:119], v[106:107]
	v_pk_mul_f32 v[120:121], v[120:121], v[108:109]
	ds_write_b128 v178, v[124:127] offset:1056
	ds_write_b128 v178, v[118:121] offset:1072
	s_waitcnt vmcnt(6)
	v_lshlrev_b32_e32 v102, 16, v74
	v_and_b32_e32 v103, 0xffff0000, v74
	v_lshlrev_b32_e32 v104, 16, v75
	v_and_b32_e32 v105, 0xffff0000, v75
	v_lshlrev_b32_e32 v106, 16, v76
	v_and_b32_e32 v107, 0xffff0000, v76
	v_lshlrev_b32_e32 v108, 16, v77
	v_and_b32_e32 v109, 0xffff0000, v77
	v_pk_mul_f32 v[124:125], v[16:17], v[110:111]
	v_pk_mul_f32 v[126:127], v[18:19], v[112:113]
	v_pk_mul_f32 v[118:119], v[20:21], v[114:115]
	v_pk_mul_f32 v[120:121], v[22:23], v[116:117]
	v_pk_fma_f32 v[124:125], v[24:25], v[2:3], v[124:125]
	v_pk_fma_f32 v[126:127], v[26:27], v[4:5], v[126:127]
	v_pk_fma_f32 v[118:119], v[30:31], v[6:7], v[118:119]
	v_pk_fma_f32 v[120:121], v[32:33], v[8:9], v[120:121]
	v_pk_fma_f32 v[124:125], v[34:35], v[10:11], v[124:125]
	v_pk_fma_f32 v[126:127], v[36:37], v[12:13], v[126:127]
	v_pk_fma_f32 v[118:119], v[38:39], v[14:15], v[118:119]
	v_pk_fma_f32 v[120:121], v[40:41], v[100:101], v[120:121]
	v_pk_fma_f32 v[124:125], v[42:43], v[102:103], v[124:125]
	v_pk_fma_f32 v[126:127], v[44:45], v[104:105], v[126:127]
	v_pk_fma_f32 v[118:119], v[46:47], v[106:107], v[118:119]
	v_pk_fma_f32 v[120:121], v[48:49], v[108:109], v[120:121]
	v_mul_f32_e32 v110, 0xbfb8aa3b, v124
	v_mul_f32_e32 v111, 0xbfb8aa3b, v125
	v_mul_f32_e32 v112, 0xbfb8aa3b, v126
	v_mul_f32_e32 v113, 0xbfb8aa3b, v127
	v_mul_f32_e32 v114, 0xbfb8aa3b, v118
	v_mul_f32_e32 v115, 0xbfb8aa3b, v119
	v_mul_f32_e32 v116, 0xbfb8aa3b, v120
	v_mul_f32_e32 v117, 0xbfb8aa3b, v121
	v_exp_f32_e32 v110, v110
	v_exp_f32_e32 v111, v111
	v_exp_f32_e32 v112, v112
	v_exp_f32_e32 v113, v113
	v_exp_f32_e32 v114, v114
	v_exp_f32_e32 v115, v115
	v_exp_f32_e32 v116, v116
	v_exp_f32_e32 v117, v117
	v_add_f32_e32 v110, 1.0, v110
	v_add_f32_e32 v111, 1.0, v111
	v_add_f32_e32 v112, 1.0, v112
	v_add_f32_e32 v113, 1.0, v113
	v_add_f32_e32 v114, 1.0, v114
	v_add_f32_e32 v115, 1.0, v115
	v_add_f32_e32 v116, 1.0, v116
	v_add_f32_e32 v117, 1.0, v117
	v_rcp_f32_e32 v110, v110
	v_rcp_f32_e32 v111, v111
	v_rcp_f32_e32 v112, v112
	v_rcp_f32_e32 v113, v113
	v_rcp_f32_e32 v114, v114
	v_rcp_f32_e32 v115, v115
	v_rcp_f32_e32 v116, v116
	v_rcp_f32_e32 v117, v117
	v_pk_mul_f32 v[124:125], v[124:125], v[110:111]
	v_pk_mul_f32 v[126:127], v[126:127], v[112:113]
	v_pk_mul_f32 v[118:119], v[118:119], v[114:115]
	v_pk_mul_f32 v[120:121], v[120:121], v[116:117]
	ds_write_b128 v178, v[124:127] offset:1584
	ds_write_b128 v178, v[118:121] offset:1600
.Lcv_done:
	s_movk_i32 s55, 0xf000
